# P4 patch + P3 schedule: prompt item at one of five positions among the block's four stream items (instead of first/last)
# baseline (speedup 1.0000x reference)
; #define LAS __attribute__((address_space(3)))
; __device__ __forceinline__ void ret_sample_item(Frame& F, int item) {
;     const int b = item >> 3, h = item & 7, w = F.wave, lane = F.lane, fr = lane & 15, fq = lane >> 4, tid = F.tid;
;     const float gam = 1.0f - exp2f(-5.0f - (float)h);
;     const float g7 = exp2f(7.0f * log2f(gam)), g8 = g7 * gam;
;     const int r0 = MP + 8 * b;
;     LAS float* qs = (LAS float*)(F.lds + SQ_OFF); LAS float* kt = (LAS float*)(F.lds + SK_OFF); LAS float* vs = (LAS float*)(F.lds + SV_OFF);
;     LAS float* part = (LAS float*)(F.lds + SPART_OFF); LAS float* pm = (LAS float*)(F.lds + SPM_OFF);
;     const int e4 = 64 * w + 4 * fr;
;     const float* S0 = F.state_ret + ((size_t)(b * NH + h) * DK + fq) * DV + e4;
;     float* S1 = F.sr_s + ((size_t)(b * NH + h) * DK + fq) * DV + e4;
;     f32x4 sa[8], sb[8];
;     const int tq8 = (tid & 255) >> 5, d0 = 8 * (tid & 31); const bool isq = tid < 256;
;     const u32x4 rawqk = *(const u32x4*)((isq ? WSP(bf16, WS_Q) : WSP(bf16, WS_K)) + (size_t)(r0 + tq8) * D + h * DK + d0);
;     const int tv = tid >> 6, e0 = 8 * (tid & 63);
;     const u32x4 rawv = *(const u32x4*)(WSP(bf16, WS_V) + (size_t)(r0 + tv) * HV + h * DV + e0);
; __device__ __forceinline__ void p3_retention(Frame& F) {
;     const bool stream_first = ((F.vcu >> 3) & 1) != 0;
;     const int mode = F.mode;
;     if (mode != 1 && stream_first) for (int it = F.vcu; it < 1024; it += F.G) ret_sample_item(F, it);
;     if (mode != 2) for (int it = F.vcu; it < 256; it += F.G) ret_prompt_item(F, it);
;     if (mode != 1 && !stream_first) for (int it = F.vcu; it < 1024; it += F.G) ret_sample_item(F, it);
.LBB0_572:
	v_readlane_b32 s2, v240, 0
	v_readlane_b32 s3, v240, 1
	s_cmp_lt_i32 s2, 4
	s_cselect_b64 s[2:3], -1, 0
	s_and_b64 s[14:15], s[2:3], s[0:1]
	s_andn2_b64 vcc, exec, s[14:15]
	s_cbranch_vccnz .LBB0_679
	v_readlane_b32 s0, v240, 5
	s_nop 0
	s_lshr_b32 s1, s0, 3
	s_mul_i32 s16, s1, 13
	s_lshr_b32 s16, s16, 6
	s_mul_i32 s16, s16, 5
	s_sub_i32 s1, s1, s16
	s_mul_i32 s16, s1, s44
	s_add_i32 s16, s16, s0
	s_min_i32 s16, s16, 0x400
	v_writelane_b32 v240, s1, 60
	s_nop 1
	v_writelane_b32 v240, s16, 61
	s_cmp_lg_u32 s1, 0
	s_cselect_b64 s[16:17], -1, 0
	s_cmpk_lt_i32 s0, 0x400
	v_readlane_b32 s1, v240, 6
	s_cselect_b64 s[18:19], -1, 0
	s_and_b64 s[0:1], s[18:19], s[16:17]
	s_andn2_b64 vcc, exec, s[0:1]
	v_lshrrev_b32_e32 v185, 4, v220
	v_bfe_u32 v182, v0, 5, 3
	v_lshrrev_b32_e32 v183, 6, v0
	v_cmp_gt_u32_e64 s[0:1], 64, v0
	v_cmp_gt_u32_e64 s[2:3], 32, v220
	v_and_b32_e32 v184, 48, v0
	s_cbranch_vccnz .LBB0_620
	s_and_b32 s6, s33, 0xffffffc0
	v_and_b32_e32 v5, 15, v0
	s_add_u32 s20, s30, 0x14400000
	v_lshl_or_b32 v2, v5, 2, s6
	s_addc_u32 s21, s31, 0
	s_lshl_b32 s6, s6, 2
	s_add_i32 s6, s6, 0
	s_add_u32 s36, s30, 0x1d400000
	v_readlane_b32 s35, v240, 43
	s_addc_u32 s37, s31, 0
	s_lshl_b32 s22, s35, 10
	v_readlane_b32 s52, v240, 27
	s_movk_i32 s7, 0x100
	v_and_b32_e32 v9, 7, v0
	v_lshrrev_b32_e32 v15, 3, v0
	s_add_i32 s22, s22, 0
	v_readlane_b32 s58, v240, 33
	v_readlane_b32 s59, v240, 34
	v_cmp_gt_u32_e32 vcc, s7, v0
	v_lshl_add_u32 v119, v220, 2, s6
	v_cmp_gt_u32_e64 s[6:7], v9, v15
	v_lshl_add_u32 v9, v9, 2, s22
	s_lshl_b32 s22, s35, 7
	v_readlane_b32 s38, v240, 5
	v_lshlrev_b32_e32 v6, 3, v0
	v_mov_b32_e32 v7, 0x12000000
	v_mov_b32_e32 v8, 0xfc00000
	v_cmp_gt_u32_e64 s[8:9], 8, v5
	v_mul_u32_u24_e32 v5, 0x410, v5
	v_lshlrev_b32_e32 v154, 2, v185
	s_add_i32 s22, s22, 0
	v_readlane_b32 s39, v240, 6
	s_mov_b32 s58, s38
	s_ashr_i32 s59, s38, 31
	s_waitcnt vmcnt(0)
	v_ashrrev_i32_e32 v3, 31, v2
	v_and_b32_e32 v4, 0xf8, v6
	v_cndmask_b32_e32 v120, v7, v8, vcc
	v_and_b32_e32 v6, 0x1f8, v6
	s_movk_i32 s10, 0x410
	v_lshrrev_b32_e32 v8, 3, v220
	v_or_b32_e32 v155, 1, v154
	v_or_b32_e32 v156, 2, v154
	v_or_b32_e32 v157, 3, v154
	v_add_u32_e32 v158, 0x2080, v9
	v_mov_b32_e32 v9, s22
	v_or_b32_e32 v5, v5, v154
	s_lshl_b64 s[38:39], s[58:59], 19
	v_mov_b32_e32 v121, 0
	v_lshlrev_b64 v[122:123], 2, v[2:3]
	v_readlane_b32 s56, v240, 31
	v_readlane_b32 s57, v240, 32
	v_readlane_b32 s60, v240, 35
	v_readlane_b32 s61, v240, 36
	s_movk_i32 s4, 0xff
	v_lshl_add_u32 v7, v4, 2, 0
	v_lshl_add_u32 v10, v6, 2, 0
	v_lshl_add_u32 v11, v182, 2, 0
	v_lshlrev_b32_e32 v12, 5, v4
	v_mul_u32_u24_e32 v13, 0x410, v182
	v_lshlrev_b32_e32 v14, 11, v183
	v_lshlrev_b32_e32 v15, 7, v185
	v_lshlrev_b32_e32 v16, 5, v155
	v_lshlrev_b32_e32 v17, 5, v156
	v_lshlrev_b32_e32 v18, 5, v157
	v_mad_u32_u24 v159, v8, s10, v9
	v_add_u32_e32 v160, 0, v5
	v_lshl_add_u32 v5, v185, 5, 0
	v_lshl_or_b32 v8, v184, 7, s38
	v_mov_b32_e32 v9, s39
	s_ashr_i32 s45, s44, 31
	s_mov_b32 s10, s58
	v_lshlrev_b32_e32 v118, 9, v185
	v_readlane_b32 s53, v240, 28
	v_readlane_b32 s54, v240, 29
	v_readlane_b32 s55, v240, 30
	v_readlane_b32 s62, v240, 37
	v_readlane_b32 s63, v240, 38
	v_readlane_b32 s64, v240, 39
	v_readlane_b32 s65, v240, 40
	v_readlane_b32 s66, v240, 41
	v_readlane_b32 s67, v240, 42
	v_lshl_add_u64 v[124:125], s[60:61], 0, v[122:123]
	v_cmp_lt_u32_e64 s[4:5], s4, v0
	v_lshl_add_u64 v[126:127], s[30:31], 0, v[120:121]
	s_mov_b32 s23, 0
	v_lshl_add_u32 v139, v2, 2, 0
	v_add_u32_e32 v161, 0x2080, v5
	v_lshl_add_u64 v[128:129], s[28:29], 0, v[8:9]
	s_lshl_b64 s[38:39], s[44:45], 19
	v_lshl_add_u64 v[130:131], s[60:61], 0, v[8:9]
	s_movk_i32 s35, 0x2000
	v_lshlrev_b32_e32 v120, 1, v4
	v_lshlrev_b32_e32 v132, 1, v6
	v_mov_b32_e32 v133, v121
	s_movk_i32 s70, 0x4000
	s_movk_i32 s71, 0x6000
	s_mov_b32 s72, 0x8000
	s_mov_b32 s73, 0xa000
	s_mov_b32 s80, 0xc000
	s_mov_b32 s81, 0xe000
	v_add_u32_e32 v162, v11, v12
	v_add_u32_e32 v163, v7, v13
	v_add_u32_e32 v164, v10, v14
	s_mov_b32 s82, 0xc2fc0000
	s_mov_b32 s83, 0x800000
	s_mov_b32 s84, 0x10000
	s_mov_b32 s85, 0x12000
	s_mov_b32 s86, 0x14000
	s_mov_b32 s87, 0x16000
	s_mov_b32 s88, 0x18000
	s_mov_b32 s89, 0x5886000
	s_mov_b32 s90, 0x5896000
	s_mov_b64 s[56:57], 0x20000
	v_add_u32_e32 v165, 0, v15
	v_lshlrev_b64 v[134:135], 1, v[2:3]
	v_add_u32_e32 v166, 0, v16
	v_add_u32_e32 v167, 0, v17
	v_add_u32_e32 v168, 0, v18
	v_mov_b32_e32 v169, 0x42800000
	v_mov_b32_e32 v170, 0x42000000
	v_writelane_b32 v240, s10, 5
	s_nop 1
	v_writelane_b32 v240, s11, 6
	s_branch .LBB0_576
.LBB0_575:
	s_or_b64 exec, exec, s[78:79]
	v_readlane_b32 s10, v240, 61
	s_add_i32 s58, s58, s44
	v_lshl_add_u64 v[128:129], v[128:129], 0, s[38:39]
	s_cmp_lt_i32 s58, s10
	v_lshl_add_u64 v[130:131], v[130:131], 0, s[38:39]
	s_cbranch_scc0 .LBB0_620

; #define LAS __attribute__((address_space(3)))
; __device__ __forceinline__ void ret_sample_item(Frame& F, int item) {
;     const int b = item >> 3, h = item & 7, w = F.wave, lane = F.lane, fr = lane & 15, fq = lane >> 4, tid = F.tid;
;     const float gam = 1.0f - exp2f(-5.0f - (float)h);
;     const float g7 = exp2f(7.0f * log2f(gam)), g8 = g7 * gam;
;     const int r0 = MP + 8 * b;
;     LAS float* qs = (LAS float*)(F.lds + SQ_OFF); LAS float* kt = (LAS float*)(F.lds + SK_OFF); LAS float* vs = (LAS float*)(F.lds + SV_OFF);
;     LAS float* part = (LAS float*)(F.lds + SPART_OFF); LAS float* pm = (LAS float*)(F.lds + SPM_OFF);
;     const int e4 = 64 * w + 4 * fr;
;     const float* S0 = F.state_ret + ((size_t)(b * NH + h) * DK + fq) * DV + e4;
;     float* S1 = F.sr_s + ((size_t)(b * NH + h) * DK + fq) * DV + e4;
;     f32x4 sa[8], sb[8];
;     const int tq8 = (tid & 255) >> 5, d0 = 8 * (tid & 31); const bool isq = tid < 256;
;     const u32x4 rawqk = *(const u32x4*)((isq ? WSP(bf16, WS_Q) : WSP(bf16, WS_K)) + (size_t)(r0 + tq8) * D + h * DK + d0);
;     const int tv = tid >> 6, e0 = 8 * (tid & 63);
;     const u32x4 rawv = *(const u32x4*)(WSP(bf16, WS_V) + (size_t)(r0 + tv) * HV + h * DV + e0);
; __device__ __forceinline__ void p3_retention(Frame& F) {
;     const bool stream_first = ((F.vcu >> 3) & 1) != 0;
;     const int mode = F.mode;
;     if (mode != 1 && stream_first) for (int it = F.vcu; it < 1024; it += F.G) ret_sample_item(F, it);
;     if (mode != 2) for (int it = F.vcu; it < 256; it += F.G) ret_prompt_item(F, it);
;     if (mode != 1 && !stream_first) for (int it = F.vcu; it < 1024; it += F.G) ret_sample_item(F, it);
; }
.LBB0_632:
	v_readlane_b32 s0, v240, 60
	s_nop 0
	s_cmp_eq_u32 s0, 4
	s_cselect_b64 s[16:17], -1, 0
	s_xor_b64 s[0:1], s[18:19], -1
	s_or_b64 s[0:1], s[16:17], s[0:1]
	s_and_b64 vcc, exec, s[0:1]
	s_cbranch_vccnz .LBB0_679
	s_andn2_b32 s33, s33, 63
	s_movk_i32 s2, 0x100
	s_add_u32 s16, s30, 0x14400000
	v_cmp_gt_u32_e32 vcc, s2, v0
	s_addc_u32 s17, s31, 0
	s_lshl_b32 s2, s33, 2
	s_add_i32 s2, s2, 0
	s_add_u32 s20, s30, 0x1d400000
	v_readlane_b32 s22, v240, 43
	s_addc_u32 s21, s31, 0
	s_lshl_b32 s18, s22, 10
	v_and_b32_e32 v9, 7, v0
	v_lshrrev_b32_e32 v15, 3, v0
	s_add_i32 s18, s18, 0
	v_and_b32_e32 v5, 15, v0
	v_cmp_gt_u32_e64 s[4:5], v9, v15
	v_lshl_add_u32 v9, v9, 2, s18
	s_lshl_b32 s18, s22, 7
	v_readlane_b32 s22, v240, 5
	v_lshl_or_b32 v2, v5, 2, s33
	v_lshlrev_b32_e32 v6, 3, v0
	v_mov_b32_e32 v7, 0x12000000
	v_mov_b32_e32 v8, 0xfc00000
	v_cmp_gt_u32_e64 s[6:7], 8, v5
	v_mul_u32_u24_e32 v5, 0x410, v5
	v_lshlrev_b32_e32 v154, 2, v185
	s_add_i32 s18, s18, 0
	v_readlane_b32 s23, v240, 6
	v_readlane_b32 s38, v240, 61
	s_mov_b32 s39, 0
	s_waitcnt vmcnt(0)
	v_ashrrev_i32_e32 v3, 31, v2
	v_readlane_b32 s52, v240, 27
	v_and_b32_e32 v4, 0xf8, v6
	v_cndmask_b32_e32 v120, v7, v8, vcc
	v_and_b32_e32 v6, 0x1f8, v6
	s_movk_i32 s10, 0x410
	v_lshrrev_b32_e32 v8, 3, v220
	v_or_b32_e32 v155, 1, v154
	v_or_b32_e32 v156, 2, v154
	v_or_b32_e32 v157, 3, v154
	v_add_u32_e32 v158, 0x2080, v9
	v_mov_b32_e32 v9, s18
	v_or_b32_e32 v5, v5, v154
	s_lshl_b64 s[22:23], s[38:39], 19
	v_mov_b32_e32 v121, 0
	v_lshlrev_b64 v[122:123], 2, v[2:3]
	v_readlane_b32 s60, v240, 35
	v_readlane_b32 s61, v240, 36
	s_movk_i32 s0, 0xff
	v_lshl_add_u32 v7, v4, 2, 0
	v_lshl_add_u32 v10, v6, 2, 0
	v_lshl_add_u32 v11, v182, 2, 0
	v_lshlrev_b32_e32 v12, 5, v4
	v_mul_u32_u24_e32 v13, 0x410, v182
	v_lshlrev_b32_e32 v14, 11, v183
	v_lshlrev_b32_e32 v15, 7, v185
	v_lshlrev_b32_e32 v16, 5, v155
	v_lshlrev_b32_e32 v17, 5, v156
	v_lshlrev_b32_e32 v18, 5, v157
	v_mad_u32_u24 v159, v8, s10, v9
	v_add_u32_e32 v160, 0, v5
	v_lshl_add_u32 v5, v185, 5, 0
	v_lshl_or_b32 v8, v184, 7, s22
	v_mov_b32_e32 v9, s23
	s_ashr_i32 s45, s44, 31
	v_readlane_b32 s10, v240, 5
	v_lshlrev_b32_e32 v118, 9, v185
	v_readlane_b32 s53, v240, 28
	v_readlane_b32 s54, v240, 29
	v_readlane_b32 s55, v240, 30
	v_readlane_b32 s56, v240, 31
	v_readlane_b32 s57, v240, 32
	v_readlane_b32 s58, v240, 33
	v_readlane_b32 s59, v240, 34
	v_readlane_b32 s62, v240, 37
	v_readlane_b32 s63, v240, 38
	v_readlane_b32 s64, v240, 39
	v_readlane_b32 s65, v240, 40
	v_readlane_b32 s66, v240, 41
	v_readlane_b32 s67, v240, 42
	v_lshl_add_u64 v[124:125], s[60:61], 0, v[122:123]
	v_cmp_lt_u32_e64 s[0:1], s0, v0
	v_lshl_add_u64 v[126:127], s[30:31], 0, v[120:121]
	s_mov_b32 s19, 0
	v_lshl_add_u32 v119, v220, 2, s2
	v_cmp_gt_u32_e64 s[2:3], 64, v0
	v_lshl_add_u32 v139, v2, 2, 0
	v_cmp_gt_u32_e64 s[8:9], 32, v220
	v_add_u32_e32 v161, 0x2080, v5
	v_lshl_add_u64 v[128:129], s[28:29], 0, v[8:9]
	s_lshl_b64 s[22:23], s[44:45], 19
	v_lshl_add_u64 v[130:131], s[60:61], 0, v[8:9]
	s_movk_i32 s33, 0x2000
	v_lshlrev_b32_e32 v120, 1, v4
	v_lshlrev_b32_e32 v132, 1, v6
	v_mov_b32_e32 v133, v121
	s_movk_i32 s35, 0x4000
	s_movk_i32 s70, 0x6000
	s_mov_b32 s71, 0x8000
	s_mov_b32 s72, 0xa000
	s_mov_b32 s73, 0xc000
	s_mov_b32 s74, 0xe000
	v_add_u32_e32 v162, v11, v12
	v_add_u32_e32 v163, v7, v13
	v_add_u32_e32 v164, v10, v14
	s_mov_b32 s75, 0xc2fc0000
	s_mov_b32 s76, 0x800000
	s_mov_b32 s77, 0x10000
	s_mov_b32 s78, 0x12000
	s_mov_b32 s79, 0x14000
	s_mov_b32 s80, 0x16000
	s_mov_b32 s81, 0x18000
	s_mov_b32 s82, 0x5886000
	s_mov_b32 s83, 0x5896000
	s_mov_b64 s[36:37], 0x20000
	v_add_u32_e32 v165, 0, v15
	v_lshlrev_b64 v[134:135], 1, v[2:3]
	v_add_u32_e32 v166, 0, v16
	v_add_u32_e32 v167, 0, v17
	v_add_u32_e32 v168, 0, v18
	v_mov_b32_e32 v169, 0x42800000
	v_mov_b32_e32 v170, 0x42000000
	v_writelane_b32 v240, s10, 5
	s_nop 1
	v_writelane_b32 v240, s11, 6
	s_branch .LBB0_635

; __device__ __forceinline__ unsigned pk2(float lo, float hi) { unsigned r; asm("v_cvt_pk_bf16_f32 %0, %1, %2" : "=v"(r) : "v"(lo), "v"(hi)); return r; }
; __device__ __forceinline__ void ret_sample_item(Frame& F, int item) {
;     ...
;     if (fq < 2) {
; #pragma unroll
;         for (int j = 0; j < 4; ++j) { const int n = 4 * fq + j;
;             f32x4 o = (f32x4){oacc[0][j], oacc[1][j], oacc[2][j], oacc[3][j]} * gam;
; #pragma unroll
;             for (int m = 0; m < 8; ++m) o += pm[n * 8 + m] * v4[m];
;             u32x2 o2; o2.x = pk2(o[0], o[1]); o2.y = pk2(o[2], o[3]);
;             *(u32x2*)(WSP(bf16, WS_O) + (size_t)(r0 + n) * HV + h * DV + e4) = o2; }
;     }
.LBB0_677:
	s_and_saveexec_b64 s[58:59], s[8:9]
	s_cbranch_execz .LBB0_634
	s_waitcnt vmcnt(8)
	ds_read_b128 v[34:37], v165 offset:34944
	ds_read_b128 v[38:41], v165 offset:34960
	v_mov_b32_e32 v42, v110
	v_mov_b32_e32 v43, v106
	s_lshl_b32 s18, s56, 1
	s_waitcnt lgkmcnt(1)
	v_pk_mul_f32 v[46:47], v[30:31], v[34:35] op_sel_hi:[1,0]
	v_pk_mul_f32 v[44:45], v[32:33], v[34:35] op_sel_hi:[1,0]
	v_pk_fma_f32 v[42:43], v[138:139], v[42:43], v[46:47] op_sel_hi:[0,1,1]
	v_mov_b32_e32 v46, v102
	v_mov_b32_e32 v47, v98
	v_pk_fma_f32 v[44:45], v[138:139], v[46:47], v[44:45] op_sel_hi:[0,1,1]
	v_pk_fma_f32 v[42:43], v[26:27], v[34:35], v[42:43] op_sel:[0,1,0]
	v_pk_fma_f32 v[34:35], v[28:29], v[34:35], v[44:45] op_sel:[0,1,0]
	v_pk_fma_f32 v[42:43], v[22:23], v[36:37], v[42:43] op_sel_hi:[1,0,1]
	v_pk_fma_f32 v[34:35], v[24:25], v[36:37], v[34:35] op_sel_hi:[1,0,1]
	v_mov_b32_e32 v36, v37
	v_pk_fma_f32 v[34:35], v[20:21], v[36:37], v[34:35] op_sel_hi:[1,0,1]
	v_pk_fma_f32 v[42:43], v[18:19], v[36:37], v[42:43] op_sel_hi:[1,0,1]
	s_waitcnt lgkmcnt(0)
	v_pk_fma_f32 v[34:35], v[16:17], v[38:39], v[34:35] op_sel_hi:[1,0,1]
	v_pk_fma_f32 v[36:37], v[14:15], v[38:39], v[42:43] op_sel_hi:[1,0,1]
	v_pk_fma_f32 v[34:35], v[12:13], v[38:39], v[34:35] op_sel:[0,1,0]
	v_pk_fma_f32 v[36:37], v[10:11], v[38:39], v[36:37] op_sel:[0,1,0]
	v_pk_fma_f32 v[34:35], v[8:9], v[40:41], v[34:35] op_sel_hi:[1,0,1]
	v_mov_b32_e32 v38, v41
	v_pk_fma_f32 v[36:37], v[6:7], v[40:41], v[36:37] op_sel_hi:[1,0,1]
	v_pk_fma_f32 v[34:35], v[4:5], v[38:39], v[34:35] op_sel_hi:[1,0,1]
	v_pk_fma_f32 v[36:37], v[2:3], v[38:39], v[36:37] op_sel_hi:[1,0,1]
	v_cvt_pk_bf16_f32 v39, v34, v35
	v_or_b32_e32 v34, s84, v154
	v_ashrrev_i32_e32 v35, 31, v34
	v_lshlrev_b64 v[34:35], 13, v[34:35]
	v_cvt_pk_bf16_f32 v38, v36, v37
	v_lshl_add_u64 v[40:41], s[20:21], 0, v[34:35]
	ds_read_b128 v[34:37], v166 offset:34944
	v_lshl_add_u64 v[40:41], v[40:41], 0, s[18:19]
	v_lshl_add_u64 v[40:41], v[40:41], 0, v[134:135]
	global_store_dwordx2 v[40:41], v[38:39], off
	ds_read_b128 v[38:41], v166 offset:34960
	s_waitcnt lgkmcnt(1)
	v_pk_mul_f32 v[42:43], v[32:33], v[34:35] op_sel_hi:[1,0]
	v_pk_mul_f32 v[44:45], v[30:31], v[34:35] op_sel_hi:[1,0]
	v_mov_b32_e32 v106, v111
	v_mov_b32_e32 v98, v103
	v_pk_fma_f32 v[44:45], v[138:139], v[106:107], v[44:45] op_sel_hi:[0,1,1]
	v_pk_fma_f32 v[42:43], v[138:139], v[98:99], v[42:43] op_sel_hi:[0,1,1]
	v_pk_fma_f32 v[44:45], v[26:27], v[34:35], v[44:45] op_sel:[0,1,0]
	v_pk_fma_f32 v[34:35], v[28:29], v[34:35], v[42:43] op_sel:[0,1,0]
	v_pk_fma_f32 v[42:43], v[22:23], v[36:37], v[44:45] op_sel_hi:[1,0,1]
	v_pk_fma_f32 v[34:35], v[24:25], v[36:37], v[34:35] op_sel_hi:[1,0,1]
	v_mov_b32_e32 v36, v37
	v_pk_fma_f32 v[34:35], v[20:21], v[36:37], v[34:35] op_sel_hi:[1,0,1]
	v_pk_fma_f32 v[42:43], v[18:19], v[36:37], v[42:43] op_sel_hi:[1,0,1]
	s_waitcnt lgkmcnt(0)
	v_pk_fma_f32 v[34:35], v[16:17], v[38:39], v[34:35] op_sel_hi:[1,0,1]
	v_pk_fma_f32 v[36:37], v[14:15], v[38:39], v[42:43] op_sel_hi:[1,0,1]
	v_pk_fma_f32 v[34:35], v[12:13], v[38:39], v[34:35] op_sel:[0,1,0]
	v_pk_fma_f32 v[36:37], v[10:11], v[38:39], v[36:37] op_sel:[0,1,0]
	v_pk_fma_f32 v[34:35], v[8:9], v[40:41], v[34:35] op_sel_hi:[1,0,1]
	v_mov_b32_e32 v38, v41
	v_pk_fma_f32 v[36:37], v[6:7], v[40:41], v[36:37] op_sel_hi:[1,0,1]
	v_pk_fma_f32 v[34:35], v[4:5], v[38:39], v[34:35] op_sel_hi:[1,0,1]
	v_pk_fma_f32 v[36:37], v[2:3], v[38:39], v[36:37] op_sel_hi:[1,0,1]
	v_cvt_pk_bf16_f32 v39, v34, v35
	v_or_b32_e32 v34, s84, v155
	v_ashrrev_i32_e32 v35, 31, v34
	v_lshlrev_b64 v[34:35], 13, v[34:35]
	v_cvt_pk_bf16_f32 v38, v36, v37
	v_lshl_add_u64 v[40:41], s[20:21], 0, v[34:35]
	ds_read_b128 v[34:37], v167 offset:34944
	v_lshl_add_u64 v[40:41], v[40:41], 0, s[18:19]
	v_lshl_add_u64 v[40:41], v[40:41], 0, v[134:135]
	global_store_dwordx2 v[40:41], v[38:39], off
	ds_read_b128 v[38:41], v167 offset:34960
	s_waitcnt lgkmcnt(1)
; __device__ __forceinline__ unsigned pk2(float lo, float hi) { unsigned r; asm("v_cvt_pk_bf16_f32 %0, %1, %2" : "=v"(r) : "v"(lo), "v"(hi)); return r; }
; __device__ __forceinline__ void ret_sample_item(Frame& F, int item) {
;     ...
;     if (fq < 2) {
; #pragma unroll
;         for (int j = 0; j < 4; ++j) { const int n = 4 * fq + j;
;             f32x4 o = (f32x4){oacc[0][j], oacc[1][j], oacc[2][j], oacc[3][j]} * gam;
; #pragma unroll
;             for (int m = 0; m < 8; ++m) o += pm[n * 8 + m] * v4[m];
;             u32x2 o2; o2.x = pk2(o[0], o[1]); o2.y = pk2(o[2], o[3]);
;             *(u32x2*)(WSP(bf16, WS_O) + (size_t)(r0 + n) * HV + h * DV + e4) = o2; }
;     }
	v_pk_mul_f32 v[44:45], v[30:31], v[34:35] op_sel_hi:[1,0]
	v_mov_b32_e32 v46, v112
	v_mov_b32_e32 v47, v108
	v_pk_mul_f32 v[42:43], v[32:33], v[34:35] op_sel_hi:[1,0]
	v_pk_fma_f32 v[44:45], v[138:139], v[46:47], v[44:45] op_sel_hi:[0,1,1]
	v_mov_b32_e32 v46, v104
	v_mov_b32_e32 v47, v100
	v_pk_fma_f32 v[42:43], v[138:139], v[46:47], v[42:43] op_sel_hi:[0,1,1]
	v_pk_fma_f32 v[44:45], v[26:27], v[34:35], v[44:45] op_sel:[0,1,0]
	v_pk_fma_f32 v[34:35], v[28:29], v[34:35], v[42:43] op_sel:[0,1,0]
	v_pk_fma_f32 v[42:43], v[22:23], v[36:37], v[44:45] op_sel_hi:[1,0,1]
	v_pk_fma_f32 v[34:35], v[24:25], v[36:37], v[34:35] op_sel_hi:[1,0,1]
	v_mov_b32_e32 v36, v37
	v_pk_fma_f32 v[34:35], v[20:21], v[36:37], v[34:35] op_sel_hi:[1,0,1]
	v_pk_fma_f32 v[42:43], v[18:19], v[36:37], v[42:43] op_sel_hi:[1,0,1]
	s_waitcnt lgkmcnt(0)
	v_pk_fma_f32 v[34:35], v[16:17], v[38:39], v[34:35] op_sel_hi:[1,0,1]
	v_pk_fma_f32 v[36:37], v[14:15], v[38:39], v[42:43] op_sel_hi:[1,0,1]
	v_pk_fma_f32 v[34:35], v[12:13], v[38:39], v[34:35] op_sel:[0,1,0]
	v_pk_fma_f32 v[36:37], v[10:11], v[38:39], v[36:37] op_sel:[0,1,0]
	v_pk_fma_f32 v[34:35], v[8:9], v[40:41], v[34:35] op_sel_hi:[1,0,1]
	v_mov_b32_e32 v38, v41
	v_pk_fma_f32 v[36:37], v[6:7], v[40:41], v[36:37] op_sel_hi:[1,0,1]
	v_pk_fma_f32 v[34:35], v[4:5], v[38:39], v[34:35] op_sel_hi:[1,0,1]
	v_pk_fma_f32 v[36:37], v[2:3], v[38:39], v[36:37] op_sel_hi:[1,0,1]
	v_cvt_pk_bf16_f32 v39, v34, v35
	v_or_b32_e32 v34, s84, v156
	v_ashrrev_i32_e32 v35, 31, v34
	v_lshlrev_b64 v[34:35], 13, v[34:35]
	v_cvt_pk_bf16_f32 v38, v36, v37
	v_lshl_add_u64 v[40:41], s[20:21], 0, v[34:35]
	ds_read_b128 v[34:37], v168 offset:34944
	v_lshl_add_u64 v[40:41], v[40:41], 0, s[18:19]
	v_lshl_add_u64 v[40:41], v[40:41], 0, v[134:135]
	global_store_dwordx2 v[40:41], v[38:39], off
	ds_read_b128 v[38:41], v168 offset:34960
	s_waitcnt lgkmcnt(1)
	v_pk_mul_f32 v[32:33], v[32:33], v[34:35] op_sel_hi:[1,0]
	v_pk_mul_f32 v[30:31], v[30:31], v[34:35] op_sel_hi:[1,0]
	v_mov_b32_e32 v108, v113
	v_mov_b32_e32 v100, v105
	v_pk_fma_f32 v[30:31], v[138:139], v[108:109], v[30:31] op_sel_hi:[0,1,1]
	v_pk_fma_f32 v[32:33], v[138:139], v[100:101], v[32:33] op_sel_hi:[0,1,1]
	v_pk_fma_f32 v[26:27], v[26:27], v[34:35], v[30:31] op_sel:[0,1,0]
	v_pk_fma_f32 v[28:29], v[28:29], v[34:35], v[32:33] op_sel:[0,1,0]
	v_pk_fma_f32 v[22:23], v[22:23], v[36:37], v[26:27] op_sel_hi:[1,0,1]
	v_pk_fma_f32 v[24:25], v[24:25], v[36:37], v[28:29] op_sel_hi:[1,0,1]
	v_mov_b32_e32 v26, v37
	v_pk_fma_f32 v[18:19], v[18:19], v[26:27], v[22:23] op_sel_hi:[1,0,1]
	v_pk_fma_f32 v[20:21], v[20:21], v[26:27], v[24:25] op_sel_hi:[1,0,1]
	s_waitcnt lgkmcnt(0)
	v_pk_fma_f32 v[14:15], v[14:15], v[38:39], v[18:19] op_sel_hi:[1,0,1]
	v_pk_fma_f32 v[16:17], v[16:17], v[38:39], v[20:21] op_sel_hi:[1,0,1]
	v_pk_fma_f32 v[10:11], v[10:11], v[38:39], v[14:15] op_sel:[0,1,0]
	v_pk_fma_f32 v[12:13], v[12:13], v[38:39], v[16:17] op_sel:[0,1,0]
	v_pk_fma_f32 v[6:7], v[6:7], v[40:41], v[10:11] op_sel_hi:[1,0,1]
	v_pk_fma_f32 v[8:9], v[8:9], v[40:41], v[12:13] op_sel_hi:[1,0,1]
	v_mov_b32_e32 v10, v41
	v_pk_fma_f32 v[2:3], v[2:3], v[10:11], v[6:7] op_sel_hi:[1,0,1]
	v_pk_fma_f32 v[4:5], v[4:5], v[10:11], v[8:9] op_sel_hi:[1,0,1]
	v_cvt_pk_bf16_f32 v2, v2, v3
	s_nop 0
	v_cvt_pk_bf16_f32 v3, v4, v5
	v_or_b32_e32 v4, s84, v157
	v_ashrrev_i32_e32 v5, 31, v4
	v_lshlrev_b64 v[4:5], 13, v[4:5]
	v_lshl_add_u64 v[4:5], s[20:21], 0, v[4:5]
	v_lshl_add_u64 v[4:5], v[4:5], 0, s[18:19]
	v_lshl_add_u64 v[4:5], v[4:5], 0, v[134:135]
	global_store_dwordx2 v[4:5], v[2:3], off
	s_branch .LBB0_634
	s_nop 0
	s_nop 0
	s_nop 0
	s_nop 0
	s_nop 0
	s_nop 0
	s_nop 0
	s_nop 0
	s_nop 0
	s_nop 0
	s_nop 0
	s_nop 0
	s_nop 0
	s_nop 0
	s_nop 0
	s_nop 0
	s_nop 0
	s_nop 0
	s_nop 0
	s_nop 0
	s_nop 0
	s_nop 0
	s_nop 0
	s_nop 0
	s_nop 0
	s_nop 0
	s_nop 0
	s_nop 0
	s_nop 0
	s_nop 0
	s_nop 0
	s_nop 0
	s_nop 0
	s_nop 0
	s_nop 0
	s_nop 0
	s_nop 0
	s_nop 0
	s_nop 0
	s_nop 0
